# work rebalancing of a phase tail: P8 sample rows handled by wave 0 of workgroups 0..127 (one extra row per CU) instead of all 8 waves of workgroups 0..15
# speedup vs baseline: 1.0094x; 1.0094x over previous
; __device__ __forceinline__ f32x4 unpack4(u32x2 u) { return (f32x4){__uint_as_float(u.x << 16), __uint_as_float(u.x & 0xffff0000u), __uint_as_float(u.y << 16), __uint_as_float(u.y & 0xffff0000u)}; }
; template <int ph>
; __device__ __forceinline__ void run_phase(const Args& args, LAS unsigned char* lds, const int G, const int bx, const bool fin = true) {
;     ...
;         for (int row = gw; row < MP; row += ngw) {
;             const int t = row & (T - 1); const int pbo = t > 0 ? -RP : 0; const float pm = t > 0 ? 1.f : 0.f;
;             POST_ROW(qr = unpack4(*(const u32x2*)(base + pbo)) * pm; qk = unpack4(*(const u32x2*)(base + pbo + 1024)) * pm; qv = unpack4(*(const u32x2*)(base + pbo + 2048)) * pm;)
;         }
;         for (int row = MP + gw; row < MT; row += ngw) {
;             const int si = row - MP;
;             POST_ROW(const float* sb = state_shift + (size_t)si * RP + c; qr = *(const f32x4*)(sb); qk = *(const f32x4*)(sb + 1024); qv = *(const f32x4*)(sb + 2048);)
;         }
.LBB0_1141:
	s_and_b32 s98, s10, 7
	s_lshr_b32 s99, s10, 3
	s_cmp_eq_u32 s98, 0
	s_cselect_b32 s10, s99, 0x80
	s_cmpk_gt_i32 s10, 0x7f
	s_cbranch_scc1 .LBB0_1144
	s_add_i32 s0, s10, 0x4000
	s_add_u32 s2, s36, 0x1000
	s_addc_u32 s3, s37, 0
	s_add_u32 s4, s36, 0x2000
	v_mov_b32_e32 v29, 0
	s_addc_u32 s5, s37, 0
	v_or_b32_e32 v0, 0x400, v28
	v_mov_b32_e32 v1, v29
	v_lshl_add_u64 v[44:45], s[2:3], 0, v[0:1]
	v_lshl_add_u64 v[46:47], s[4:5], 0, v[0:1]
	v_or_b32_e32 v0, 0x800, v28
	v_lshl_add_u64 v[48:49], s[2:3], 0, v[0:1]
	v_lshl_add_u64 v[50:51], s[4:5], 0, v[0:1]
	v_or_b32_e32 v0, 0xc00, v28
	s_ashr_i32 s1, s0, 31
	v_lshl_add_u64 v[32:33], s[2:3], 0, v[28:29]
	v_lshl_add_u64 v[52:53], s[2:3], 0, v[0:1]
	s_lshl_b64 s[2:3], s[0:1], 11
	v_lshl_add_u64 v[30:31], s[36:37], 0, v[28:29]
	v_lshl_add_u64 v[36:37], s[50:51], 0, v[28:29]
	v_readlane_b32 s36, v229, 32
	s_add_u32 s16, s34, s2
	v_readlane_b32 s37, v229, 33
	v_readlane_b32 s38, v229, 34
	v_readlane_b32 s39, v229, 35
	v_readlane_b32 s40, v229, 36
	v_readlane_b32 s41, v229, 37
	v_readlane_b32 s42, v229, 38
	v_readlane_b32 s43, v229, 39
	v_readlane_b32 s44, v229, 40
	v_readlane_b32 s45, v229, 41
	v_readlane_b32 s46, v229, 42
	v_readlane_b32 s47, v229, 43
	v_readlane_b32 s48, v229, 44
	v_readlane_b32 s49, v229, 45
	v_readlane_b32 s50, v229, 46
	v_readlane_b32 s51, v229, 47
	s_addc_u32 s17, s35, s3
	s_ashr_i32 s19, s18, 31
	v_lshl_add_u64 v[38:39], s[36:37], 0, v[28:29]
	v_lshl_add_u64 v[40:41], s[38:39], 0, v[28:29]
	v_lshl_add_u64 v[42:43], s[40:41], 0, v[28:29]
	v_readlane_b32 s36, v229, 0
	s_lshl_b64 s[20:21], s[18:19], 11
	s_mul_hi_i32 s1, s0, 0x1a00
	s_mulk_i32 s0, 0x1a00
	v_readlane_b32 s37, v229, 1
	v_readlane_b32 s38, v229, 2
	v_readlane_b32 s48, v229, 12
	v_readlane_b32 s49, v229, 13
	s_add_u32 s22, s34, s0
	v_lshl_add_u64 v[34:35], s[4:5], 0, v[28:29]
	v_lshl_add_u64 v[54:55], s[4:5], 0, v[0:1]
	v_lshl_add_u64 v[56:57], s[48:49], 0, v[28:29]
	v_lshlrev_b32_e32 v28, 3, v63
	s_addc_u32 s23, s35, s1
	s_mov_b32 s19, 0x9e01000
	v_mov_b32_e32 v138, 0x3400
	s_movk_i32 s24, 0x1000
	s_movk_i32 s25, 0x2000
	s_mov_b32 s26, 0x1ac00000
	s_mov_b32 s27, 0x5d00000
	v_mov_b32_e32 v139, 0x3a27c5ac
	s_mov_b32 s28, 0xf800000
	v_mov_b32_e32 v140, 0x260
	s_mov_b32 s29, 0x1cd00000
	s_mov_b32 s36, 0x14900000
	s_mov_b32 s37, 0x16a00000
	s_mov_b32 s38, 0x7d80000
	v_readlane_b32 s39, v229, 3
	v_readlane_b32 s40, v229, 4
	v_readlane_b32 s41, v229, 5
	v_readlane_b32 s42, v229, 6
	v_readlane_b32 s43, v229, 7
	v_readlane_b32 s44, v229, 8
	v_readlane_b32 s45, v229, 9
	v_readlane_b32 s46, v229, 10
	v_readlane_b32 s47, v229, 11
	v_readlane_b32 s50, v229, 14
	v_readlane_b32 s51, v229, 15
